# lnpass inside phase 6, rows split: scan WGs [0,1664), attention WGs the rest after their GEMM
# baseline (speedup 1.0000x reference)
;     __device__ __forceinline__ const float* in(int i) const { return (const float*)ptr(i); }
;     __device__ __forceinline__ unsigned char* ws() const { return (unsigned char*)ptr(37); }
; #define ws (p.ws())
; __device__ __forceinline__ void phase_lnpass(const Ctx& p) {
;     const int tid = threadIdx.x, c8 = tid & 7, h = (tid >> 3) & 7, rr = tid >> 6, c = h * 64 + 8 * c8;
;     const bf16_t* ZRW = (const bf16_t*)(p.ws() + WS_ZRW); const bf16_t* AB = (const bf16_t*)(p.ws() + WS_ABUF); const bf16_t* GG = (const bf16_t*)(p.ws() + WS_GG);
;     bf16_t* ORW = (bf16_t*)(p.ws() + WS_ORW);
;     float mur[8], muk[8], muv[8], kac[8], rkc[8], lg[8], lb[8];
; #pragma unroll
;     for (int e = 0; e < 8; ++e) { mur[e] = p.in(17)[c + e]; muk[e] = p.in(17)[512 + c + e]; muv[e] = p.in(17)[1024 + c + e]; kac[e] = p.in(24)[c + e]; rkc[e] = p.in(25)[c + e]; lg[e] = p.in(26)[c + e]; lb[e] = p.in(27)[c + e]; }
;     struct LR { u32x4 zr, zrp, zk, zkp, zv, zvp, ab, gg, yy; };
;     auto ldrow = [&](LR& L, int row) {
;         const int rp = row > 0 ? row - 1 : 0;
;         L.zr = *(const u32x4*)(ZRW + (size_t)row * SHW + c); L.zrp = *(const u32x4*)(ZRW + (size_t)rp * SHW + c);
;         L.zk = *(const u32x4*)(ZRW + (size_t)row * SHW + 512 + c); L.zkp = *(const u32x4*)(ZRW + (size_t)rp * SHW + 512 + c);
;         L.zv = *(const u32x4*)(ZRW + (size_t)row * SHW + 1024 + c); L.zvp = *(const u32x4*)(ZRW + (size_t)rp * SHW + 1024 + c);
;         L.ab = *(const u32x4*)(AB + (size_t)row * 512 + c); L.gg = *(const u32x4*)(GG + (size_t)row * 512 + c); L.yy = *(const u32x4*)(ORW + (size_t)row * 512 + c);
;     };
;     LR La, Lb;
;     if ((int)blockIdx.x < MR / 8) ldrow(La, blockIdx.x * 8 + rr);
.Lln_sync_done:
	s_or_b64 exec, exec, s[2:3]
	s_waitcnt lgkmcnt(0)
	s_barrier
	s_movk_i32 s72, 0x80
	s_add_i32 s2, 0, 0x23528
	s_waitcnt vmcnt(0)
	v_mov_b32_e32 v0, s2
	ds_read_b64 v[0:1], v0
	s_add_i32 s2, 0, 0x23488
	v_mov_b32_e32 v2, s2
	s_add_i32 s6, 0, 0x234c0
	ds_read_b64 v[8:9], v2
	s_waitcnt lgkmcnt(0)
	v_readfirstlane_b32 s2, v0
	v_mov_b32_e32 v0, s6
	s_add_i32 s6, 0, 0x234d0
	v_mov_b32_e32 v4, s6
	v_readfirstlane_b32 s3, v1
	ds_read_b128 v[0:3], v0
	ds_read_b128 v[4:7], v4
	v_readfirstlane_b32 s12, v8
	v_readfirstlane_b32 s13, v9
	s_cmpk_gt_i32 s28, 0x67f
	s_waitcnt lgkmcnt(1)
	v_readfirstlane_b32 s14, v0
	v_readfirstlane_b32 s15, v1
	v_readfirstlane_b32 s16, v2
	v_readfirstlane_b32 s17, v3
	s_waitcnt lgkmcnt(0)
	v_readfirstlane_b32 s10, v4
	v_readfirstlane_b32 s11, v5
	v_readfirstlane_b32 s8, v6
	v_readfirstlane_b32 s9, v7
	s_cbranch_scc1 .Lln_done
	v_lshlrev_b32_e32 v0, 3, v180
	v_and_b32_e32 v56, 0x1f8, v0
	v_mov_b32_e32 v141, 0
	v_lshlrev_b32_e32 v140, 2, v56
	v_lshl_add_u64 v[32:33], s[12:13], 0, v[140:141]
	global_load_dwordx4 v[0:3], v140, s[12:13] offset:16
	global_load_dwordx4 v[4:7], v140, s[12:13]
	global_load_dwordx4 v[8:11], v140, s[12:13] offset:2064
	global_load_dwordx4 v[12:15], v140, s[12:13] offset:2048
	global_load_dwordx4 v[16:19], v140, s[14:15] offset:16
	global_load_dwordx4 v[20:23], v140, s[14:15]
	global_load_dwordx4 v[24:27], v140, s[16:17] offset:16
	global_load_dwordx4 v[28:31], v140, s[16:17]
	s_movk_i32 s12, 0x1000
	v_add_co_u32_e32 v60, vcc, s12, v32
	s_mov_b64 s[6:7], 0x1000
	s_nop 0
	v_addc_co_u32_e32 v61, vcc, 0, v33, vcc
	v_lshl_add_u64 v[58:59], v[32:33], 0, s[6:7]
	global_load_dwordx4 v[32:35], v[60:61], off
	global_load_dwordx4 v[36:39], v[58:59], off offset:16
	global_load_dwordx4 v[40:43], v140, s[10:11] offset:16
	global_load_dwordx4 v[44:47], v140, s[10:11]
	global_load_dwordx4 v[48:51], v140, s[8:9] offset:16
	global_load_dwordx4 v[52:55], v140, s[8:9]
	s_add_u32 s8, s2, 0x8340000
	s_addc_u32 s9, s3, 0
	s_add_u32 s10, s2, 0x4240000
	s_addc_u32 s11, s3, 0
	s_add_u32 s14, s2, 0x3200000
	v_lshrrev_b32_e32 v152, 6, v180
	s_addc_u32 s15, s3, 0
	s_lshl_b32 s12, s28, 3
	v_add_u32_e32 v58, s12, v152
	v_max_i32_e32 v57, 1, v58
	s_movk_i32 s13, 0xe00
	v_mov_b64_e32 v[60:61], s[8:9]
	v_add_u32_e32 v57, -1, v57
	v_mad_i64_i32 v[62:63], s[16:17], v58, s13, v[60:61]
	v_lshlrev_b32_e32 v140, 1, v56
	v_lshl_add_u64 v[62:63], v[62:63], 0, v[140:141]
	v_mad_u64_u32 v[60:61], s[16:17], v57, s13, v[60:61]
	v_ashrrev_i32_e32 v59, 31, v58
	v_lshl_add_u64 v[60:61], v[60:61], 0, v[140:141]
	global_load_dwordx4 v[104:107], v[62:63], off
	global_load_dwordx4 v[108:111], v[62:63], off offset:1024
	global_load_dwordx4 v[124:127], v[60:61], off
	global_load_dwordx4 v[92:95], v[62:63], off offset:2048
	global_load_dwordx4 v[116:119], v[60:61], off offset:1024
	global_load_dwordx4 v[120:123], v[60:61], off offset:2048
	v_lshlrev_b64 v[58:59], 10, v[58:59]
	v_lshl_add_u64 v[60:61], s[14:15], 0, v[58:59]
	v_lshl_add_u64 v[62:63], s[10:11], 0, v[58:59]
	v_lshl_add_u64 v[58:59], s[2:3], 0, v[58:59]
	v_lshl_add_u64 v[60:61], v[60:61], 0, v[140:141]
	v_lshl_add_u64 v[58:59], v[58:59], 0, v[140:141]
	v_lshl_add_u64 v[62:63], v[62:63], 0, v[140:141]
	global_load_dwordx4 v[112:115], v[60:61], off
	global_load_dwordx4 v[100:103], v[62:63], off
	global_load_dwordx4 v[96:99], v[58:59], off
	v_lshl_add_u64 v[146:147], s[2:3], 0, v[140:141]
	s_add_i32 s2, s28, s72
	v_lshl_add_u64 v[142:143], s[14:15], 0, v[140:141]
	v_lshl_add_u64 v[144:145], s[10:11], 0, v[140:141]
	v_lshl_add_u64 v[148:149], s[8:9], 0, v[140:141]
	s_lshl_b32 s14, s2, 3
	s_lshl_b32 s15, s72, 3
	s_movk_i32 s16, 0x4000
	s_movk_i32 s17, 0x3fff
	s_add_i32 s18, 0, 0x23428
	s_movk_i32 s19, 0x1c00
	v_lshlrev_b32_e32 v140, 2, v56
	v_mov_b32_e32 v153, 0x3a27c5ac
	s_mov_b32 s20, 0xf800000
	v_mov_b32_e32 v154, 0x260
	v_mov_b32_e32 v155, 0xfff
	s_mov_b32 s21, s28
	s_branch .Lln_c

; __device__ __forceinline__ void phase_lnpass(const Ctx& p) {
;     ...
;     auto ldrow = [&](LR& L, int row) {
;         const int rp = row > 0 ? row - 1 : 0;
;         L.zr = *(const u32x4*)(ZRW + (size_t)row * SHW + c); L.zrp = *(const u32x4*)(ZRW + (size_t)rp * SHW + c);
;         L.zk = *(const u32x4*)(ZRW + (size_t)row * SHW + 512 + c); L.zkp = *(const u32x4*)(ZRW + (size_t)rp * SHW + 512 + c);
;         L.zv = *(const u32x4*)(ZRW + (size_t)row * SHW + 1024 + c); L.zvp = *(const u32x4*)(ZRW + (size_t)rp * SHW + 1024 + c);
;         L.ab = *(const u32x4*)(AB + (size_t)row * 512 + c); L.gg = *(const u32x4*)(GG + (size_t)row * 512 + c); L.yy = *(const u32x4*)(ORW + (size_t)row * 512 + c);
;     };
;     LR La, Lb;
;     if ((int)blockIdx.x < MR / 8) ldrow(La, blockIdx.x * 8 + rr);
;     for (int it = blockIdx.x; it < MR / 8; it += gridDim.x) {
;         const int row = it * 8 + rr;
;         const bool more = it + (int)gridDim.x < MR / 8;
;         if (more) ldrow(Lb, (it + gridDim.x) * 8 + rr);
.Lln_c:
	s_add_i32 s21, s21, s72
	s_cmpk_gt_i32 s21, 0x67f
	s_cselect_b64 s[8:9], -1, 0
	s_and_b64 vcc, exec, s[8:9]
	s_cbranch_vccnz .Lln_d
	v_add_u32_e32 v80, s14, v152
	v_max_i32_e32 v56, 1, v80
	v_add_u32_e32 v56, -1, v56
	v_mad_i64_i32 v[68:69], s[2:3], v80, s13, v[148:149]
	v_mad_u64_u32 v[76:77], s[2:3], v56, s13, v[148:149]
	global_load_dwordx4 v[56:59], v[68:69], off
	global_load_dwordx4 v[64:67], v[68:69], off offset:1024
	global_load_dwordx4 v[60:63], v[76:77], off
	global_load_dwordx4 v[72:75], v[68:69], off offset:2048
	s_nop 0
	global_load_dwordx4 v[68:71], v[76:77], off offset:1024
	s_nop 0
	global_load_dwordx4 v[76:79], v[76:77], off offset:2048
	v_ashrrev_i32_e32 v81, 31, v80
	v_lshlrev_b64 v[88:89], 10, v[80:81]
	v_lshl_add_u64 v[80:81], v[142:143], 0, v[88:89]
	v_lshl_add_u64 v[84:85], v[144:145], 0, v[88:89]
	v_lshl_add_u64 v[88:89], v[146:147], 0, v[88:89]
	global_load_dwordx4 v[80:83], v[80:81], off
	s_nop 0
	global_load_dwordx4 v[84:87], v[84:85], off
	s_nop 0
	global_load_dwordx4 v[88:91], v[88:89], off

;     __device__ __forceinline__ const float* in(int i) const { return (const float*)ptr(i); }
;     __device__ __forceinline__ unsigned char* ws() const { return (unsigned char*)ptr(37); }
; #define ws (p.ws())
; __device__ __forceinline__ void phase_lnpass(const Ctx& p) {
;     const int tid = threadIdx.x, c8 = tid & 7, h = (tid >> 3) & 7, rr = tid >> 6, c = h * 64 + 8 * c8;
;     const bf16_t* ZRW = (const bf16_t*)(p.ws() + WS_ZRW); const bf16_t* AB = (const bf16_t*)(p.ws() + WS_ABUF); const bf16_t* GG = (const bf16_t*)(p.ws() + WS_GG);
;     bf16_t* ORW = (bf16_t*)(p.ws() + WS_ORW);
;     float mur[8], muk[8], muv[8], kac[8], rkc[8], lg[8], lb[8];
; #pragma unroll
;     for (int e = 0; e < 8; ++e) { mur[e] = p.in(17)[c + e]; muk[e] = p.in(17)[512 + c + e]; muv[e] = p.in(17)[1024 + c + e]; kac[e] = p.in(24)[c + e]; rkc[e] = p.in(25)[c + e]; lg[e] = p.in(26)[c + e]; lb[e] = p.in(27)[c + e]; }
;     struct LR { u32x4 zr, zrp, zk, zkp, zv, zvp, ab, gg, yy; };
;     auto ldrow = [&](LR& L, int row) {
;         const int rp = row > 0 ? row - 1 : 0;
;         L.zr = *(const u32x4*)(ZRW + (size_t)row * SHW + c); L.zrp = *(const u32x4*)(ZRW + (size_t)rp * SHW + c);
;         L.zk = *(const u32x4*)(ZRW + (size_t)row * SHW + 512 + c); L.zkp = *(const u32x4*)(ZRW + (size_t)rp * SHW + 512 + c);
;         L.zv = *(const u32x4*)(ZRW + (size_t)row * SHW + 1024 + c); L.zvp = *(const u32x4*)(ZRW + (size_t)rp * SHW + 1024 + c);
;         L.ab = *(const u32x4*)(AB + (size_t)row * 512 + c); L.gg = *(const u32x4*)(GG + (size_t)row * 512 + c); L.yy = *(const u32x4*)(ORW + (size_t)row * 512 + c);
;     };
;     LR La, Lb;
;     if ((int)blockIdx.x < MR / 8) ldrow(La, blockIdx.x * 8 + rr);
.LBB0_1868:
	s_waitcnt vmcnt(0)
	s_barrier
	v_cmp_eq_u32_e32 vcc, 0, v180
	s_and_saveexec_b64 s[2:3], vcc
	s_cbranch_execz .Lln2_sync_done
	v_mov_b32_e32 v0, 0x23528
	ds_read_b64 v[0:1], v0
	s_waitcnt lgkmcnt(0)
	v_readfirstlane_b32 s4, v0
	v_readfirstlane_b32 s5, v1
	s_nop 4
	s_add_u32 s4, s4, 0x3180300
	s_addc_u32 s5, s5, 0
	v_mov_b32_e32 v0, 0
.Lln2_spin:
	global_load_dword v1, v0, s[4:5] sc1
	s_waitcnt vmcnt(0)
	v_cmp_gt_u32_e32 vcc, 0x80, v1
	s_cbranch_vccz .Lln2_spin_done
	s_sleep 8
	s_branch .Lln2_spin
.Lln2_spin_done:
	buffer_inv sc1
	s_waitcnt vmcnt(0)
.Lln2_sync_done:
	s_or_b64 exec, exec, s[2:3]
	s_waitcnt lgkmcnt(0)
	s_barrier
	s_movk_i32 s72, 0x80
	s_add_i32 s71, s28, 0x600
	s_add_i32 s2, 0, 0x23528
	s_waitcnt vmcnt(0)
	v_mov_b32_e32 v0, s2
	ds_read_b64 v[0:1], v0
	s_add_i32 s2, 0, 0x23488
	v_mov_b32_e32 v2, s2
	s_add_i32 s6, 0, 0x234c0
	ds_read_b64 v[8:9], v2
	s_waitcnt lgkmcnt(0)
	v_readfirstlane_b32 s2, v0
	v_mov_b32_e32 v0, s6
	s_add_i32 s6, 0, 0x234d0
	v_mov_b32_e32 v4, s6
	v_readfirstlane_b32 s3, v1
	ds_read_b128 v[0:3], v0
	ds_read_b128 v[4:7], v4
	v_readfirstlane_b32 s12, v8
	v_readfirstlane_b32 s13, v9
	s_cmpk_gt_i32 s71, 0x80f
	s_waitcnt lgkmcnt(1)
	v_readfirstlane_b32 s14, v0
	v_readfirstlane_b32 s15, v1
	v_readfirstlane_b32 s16, v2
	v_readfirstlane_b32 s17, v3
	s_waitcnt lgkmcnt(0)
	v_readfirstlane_b32 s10, v4
	v_readfirstlane_b32 s11, v5
	v_readfirstlane_b32 s8, v6
	v_readfirstlane_b32 s9, v7
	s_cbranch_scc1 .Lln2_done
	v_lshlrev_b32_e32 v0, 3, v180
	v_and_b32_e32 v56, 0x1f8, v0
	v_mov_b32_e32 v141, 0
	v_lshlrev_b32_e32 v140, 2, v56
	v_lshl_add_u64 v[32:33], s[12:13], 0, v[140:141]
	global_load_dwordx4 v[0:3], v140, s[12:13] offset:16
	global_load_dwordx4 v[4:7], v140, s[12:13]
	global_load_dwordx4 v[8:11], v140, s[12:13] offset:2064
	global_load_dwordx4 v[12:15], v140, s[12:13] offset:2048
	global_load_dwordx4 v[16:19], v140, s[14:15] offset:16
	global_load_dwordx4 v[20:23], v140, s[14:15]
	global_load_dwordx4 v[24:27], v140, s[16:17] offset:16
	global_load_dwordx4 v[28:31], v140, s[16:17]
	s_movk_i32 s12, 0x1000
	v_add_co_u32_e32 v60, vcc, s12, v32
	s_mov_b64 s[6:7], 0x1000
	s_nop 0
	v_addc_co_u32_e32 v61, vcc, 0, v33, vcc
	v_lshl_add_u64 v[58:59], v[32:33], 0, s[6:7]
	global_load_dwordx4 v[32:35], v[60:61], off
	global_load_dwordx4 v[36:39], v[58:59], off offset:16
	global_load_dwordx4 v[40:43], v140, s[10:11] offset:16
	global_load_dwordx4 v[44:47], v140, s[10:11]
	global_load_dwordx4 v[48:51], v140, s[8:9] offset:16
	global_load_dwordx4 v[52:55], v140, s[8:9]
	s_add_u32 s8, s2, 0x8340000
	s_addc_u32 s9, s3, 0
	s_add_u32 s10, s2, 0x4240000
	s_addc_u32 s11, s3, 0
	s_add_u32 s14, s2, 0x3200000
	v_lshrrev_b32_e32 v152, 6, v180
	s_addc_u32 s15, s3, 0
	s_lshl_b32 s12, s71, 3
	v_add_u32_e32 v58, s12, v152
	v_max_i32_e32 v57, 1, v58
	s_movk_i32 s13, 0xe00
	v_mov_b64_e32 v[60:61], s[8:9]
	v_add_u32_e32 v57, -1, v57
	v_mad_i64_i32 v[62:63], s[16:17], v58, s13, v[60:61]
	v_lshlrev_b32_e32 v140, 1, v56
	v_lshl_add_u64 v[62:63], v[62:63], 0, v[140:141]
	v_mad_u64_u32 v[60:61], s[16:17], v57, s13, v[60:61]
	v_ashrrev_i32_e32 v59, 31, v58
	v_lshl_add_u64 v[60:61], v[60:61], 0, v[140:141]
	global_load_dwordx4 v[104:107], v[62:63], off
	global_load_dwordx4 v[108:111], v[62:63], off offset:1024
	global_load_dwordx4 v[124:127], v[60:61], off
	global_load_dwordx4 v[92:95], v[62:63], off offset:2048
	global_load_dwordx4 v[116:119], v[60:61], off offset:1024
	global_load_dwordx4 v[120:123], v[60:61], off offset:2048
	v_lshlrev_b64 v[58:59], 10, v[58:59]
	v_lshl_add_u64 v[60:61], s[14:15], 0, v[58:59]
	v_lshl_add_u64 v[62:63], s[10:11], 0, v[58:59]
	v_lshl_add_u64 v[58:59], s[2:3], 0, v[58:59]
	v_lshl_add_u64 v[60:61], v[60:61], 0, v[140:141]
	v_lshl_add_u64 v[58:59], v[58:59], 0, v[140:141]
	v_lshl_add_u64 v[62:63], v[62:63], 0, v[140:141]
	global_load_dwordx4 v[112:115], v[60:61], off
	global_load_dwordx4 v[100:103], v[62:63], off
	global_load_dwordx4 v[96:99], v[58:59], off
	v_lshl_add_u64 v[146:147], s[2:3], 0, v[140:141]
	s_add_i32 s2, s71, s72
	v_lshl_add_u64 v[142:143], s[14:15], 0, v[140:141]
	v_lshl_add_u64 v[144:145], s[10:11], 0, v[140:141]
	v_lshl_add_u64 v[148:149], s[8:9], 0, v[140:141]
	s_lshl_b32 s14, s2, 3
	s_lshl_b32 s15, s72, 3
	s_movk_i32 s16, 0x4000
	s_movk_i32 s17, 0x3fff
	s_add_i32 s18, 0, 0x23428
	s_movk_i32 s19, 0x1c00
	v_lshlrev_b32_e32 v140, 2, v56
	v_mov_b32_e32 v153, 0x3a27c5ac
	s_mov_b32 s20, 0xf800000
	v_mov_b32_e32 v154, 0x260
	v_mov_b32_e32 v155, 0xfff
	s_mov_b32 s21, s71
	s_branch .Lln2_c

; __device__ __forceinline__ unsigned xb_ld(unsigned* p)              { return __hip_atomic_load(p, __ATOMIC_RELAXED, __HIP_MEMORY_SCOPE_AGENT); }
; __device__ __forceinline__ void xcd_barrier_complete(unsigned* bar, unsigned x, unsigned& nloc, unsigned& nx) {
;     const unsigned G = gridDim.x * gridDim.y * gridDim.z;
;     unsigned sum, cnt, mine, sp = 0u;
;     for (;;) {
;         sum = 0u; cnt = 0u; mine = 0u;
; #pragma unroll
;         for (unsigned j = 0; j < 16; ++j) { const unsigned c = xb_ld(&bar[XB_XCNT(j)]); sum += c; cnt += (c > 0u) ? 1u : 0u; mine = (j == x) ? c : mine; }
;         if (sum == G) break;
;         __builtin_amdgcn_s_sleep(1);
;         if ((++sp & 255u) == 0u) { if (xb_ld(&bar[XB_TMO])) break; if (sp > XB_SPIN_CAP) { atomicAdd(&bar[XB_TMO], 1u); break; } }
;     }
;     nloc = mine > 0u ? mine : 1u; nx = cnt > 0u ? cnt : 1u;
; }
; __device__ __forceinline__ void xcd_barrier(const XcdBarrier& b) {
;     asm volatile("s_waitcnt vmcnt(0)" ::: "memory");
;     __syncthreads();
;     if (threadIdx.x == 0) {
;         unsigned* bar = b.bar;
;         __builtin_amdgcn_s_waitcnt(0);
;         unsigned nloc = b.st[0], nx = b.st[1];
;         if (nloc == 0u) { xcd_barrier_complete(bar, b.x, nloc, nx); b.st[0] = nloc; b.st[1] = nx; }
.Lln2_done:
.LBB0_1869:
	s_cmp_gt_u32 s37, 7
	s_cselect_b64 s[2:3], -1, 0
	s_and_b64 s[2:3], s[40:41], s[2:3]
	s_andn2_b64 vcc, exec, s[2:3]
	s_cbranch_vccnz .LBB0_1941
	s_waitcnt vmcnt(0)
	v_readlane_b32 s0, v238, 0
	v_readlane_b32 s1, v238, 1
	s_waitcnt vmcnt(0) lgkmcnt(0)
	s_barrier
	s_and_saveexec_b64 s[2:3], s[0:1]
	s_cbranch_execz .LBB0_1940
	s_add_i32 s4, 0, 0x23800
	v_mov_b32_e32 v0, s4
	s_waitcnt vmcnt(0) expcnt(0) lgkmcnt(0)
	ds_read_b32 v2, v0
	s_add_i32 s4, 0, 0x23804
	v_mov_b32_e32 v0, s4
	ds_read_b32 v0, v0
	s_waitcnt lgkmcnt(1)
	v_cmp_ne_u32_e32 vcc, 0, v2
	s_cbranch_vccnz .LBB0_1886
	s_add_u32 s4, s30, 0x3181200
	s_addc_u32 s5, s31, 0
	s_add_u32 s6, s30, 0x3181400
	s_addc_u32 s7, s31, 0
	s_add_u32 s8, s30, 0x3181500
	s_addc_u32 s9, s31, 0
	s_add_u32 s10, s30, 0x3181600
	s_addc_u32 s11, s31, 0
	s_add_u32 s12, s30, 0x3181700
	s_addc_u32 s13, s31, 0
	s_add_u32 s14, s30, 0x3181800
	s_addc_u32 s15, s31, 0
	s_add_u32 s16, s30, 0x3181900
	s_addc_u32 s17, s31, 0
	s_add_u32 s18, s30, 0x3181a00
	s_addc_u32 s19, s31, 0
	s_add_u32 s20, s30, 0x3181b00
	s_addc_u32 s21, s31, 0
	s_add_u32 s22, s30, 0x3181c00
	s_addc_u32 s23, s31, 0
	s_add_u32 s24, s30, 0x3181d00
	s_addc_u32 s25, s31, 0
	s_add_u32 s26, s30, 0x3181e00
	s_addc_u32 s27, s31, 0
	s_add_u32 s40, s30, 0x3181f00
	s_addc_u32 s41, s31, 0
	s_add_u32 s42, s30, 0x3182000
	s_addc_u32 s43, s31, 0
	s_add_u32 s44, s30, 0x3182100
	s_addc_u32 s45, s31, 0
	s_add_u32 s46, s30, 0x3182200
	s_addc_u32 s47, s31, 0
	s_mul_i32 s33, s39, s73
	s_add_u32 s48, s30, 0x3182300
	s_mul_i32 s33, s33, s38
	s_addc_u32 s49, s31, 0
	s_mov_b32 s34, 1
	v_mov_b32_e32 v16, 0
	s_branch .LBB0_1874
